# stack: + phase-2 f32 norm loop unrolled with all 8 rows' (nt) loads issued up front
# speedup vs baseline: 1.0126x; 1.0047x over previous
.LBB0_250:
	v_lshrrev_b32_e32 v16, 8, v110
	v_mul_hi_i32_i24_e32 v17, 0x9000, v16
	v_mul_i32_i24_e32 v16, 0x9000, v16
	v_lshlrev_b32_e32 v86, 3, v110
	v_lshl_add_u64 v[16:17], s[96:97], 0, v[16:17]
	v_ashrrev_i32_e32 v87, 31, v86
	v_readlane_b32 s36, v254, 11
	v_lshl_add_u64 v[20:21], v[16:17], 0, s[30:31]
	v_lshlrev_b64 v[32:33], 12, v[86:87]
	v_readlane_b32 s37, v254, 12
	v_lshl_add_u64 v[18:19], v[20:21], 0, v[66:67]
	v_lshl_add_u64 v[22:23], v[20:21], 0, v[68:69]
	v_lshl_add_u64 v[32:33], s[36:37], 0, v[32:33]
	v_lshl_add_u64 v[28:29], v[16:17], 0, v[66:67]
	global_load_dwordx4 v[88:91], v[18:19], off
	s_nop 0
	global_load_dwordx4 v[16:19], v[28:29], off
	global_load_dwordx4 v[92:95], v[22:23], off
	v_lshl_add_u64 v[22:23], v[20:21], 0, v[70:71]
	v_lshl_add_u64 v[20:21], v[20:21], 0, v[72:73]
	v_lshl_add_u64 v[32:33], v[32:33], 0, v[82:83]
	global_load_dwordx4 v[96:99], v[22:23], off
	global_load_dwordx4 v[100:103], v[20:21], off
	s_nop 0
	global_load_dwordx4 v[20:23], v[28:29], off offset:1024
	global_load_dwordx4 v[24:27], v[28:29], off offset:2048
	s_nop 0
	global_load_dwordx4 v[28:31], v[28:29], off offset:3072
	s_nop 0
	v_ashrrev_i32_e32 v81, 31, v80
	v_readlane_b32 s48, v254, 23
	v_readlane_b32 s49, v254, 24
	v_readlane_b32 s50, v254, 25
	v_readlane_b32 s51, v254, 26
	v_lshlrev_b64 v[84:85], 12, v[80:81]
	v_lshlrev_b64 v[86:87], 11, v[86:87]
	v_lshl_add_u64 v[84:85], v[78:79], 0, v[84:85]
	v_lshl_add_u64 v[86:87], v[76:77], 0, v[86:87]
	v_readlane_b32 s38, v254, 13
	v_readlane_b32 s39, v254, 14
	v_readlane_b32 s40, v254, 15
	v_readlane_b32 s41, v254, 16
	v_readlane_b32 s42, v254, 17
	v_readlane_b32 s43, v254, 18
	v_readlane_b32 s44, v254, 19
	v_readlane_b32 s45, v254, 20
	v_readlane_b32 s46, v254, 21
	v_readlane_b32 s47, v254, 22
	global_load_dwordx4 v[60:63], v[32:33], off nt
	global_load_dwordx4 v[56:59], v[32:33], off offset:1024 nt
	global_load_dwordx4 v[44:47], v[32:33], off offset:2048 nt
	global_load_dwordx4 v[36:39], v[32:33], off offset:3072 nt
	s_mov_b64 s[6:7], 0x1000
	v_lshl_add_u64 v[112:113], v[84:85], 0, s[6:7]
	global_load_dwordx4 v[32:35], v[112:113], off nt
	global_load_dwordx4 v[40:43], v[112:113], off offset:1024 nt
	global_load_dwordx4 v[48:51], v[112:113], off offset:2048 nt
	global_load_dwordx4 v[52:55], v[112:113], off offset:3072 nt
	s_mov_b64 s[6:7], 0x2000
	v_lshl_add_u64 v[114:115], v[84:85], 0, s[6:7]
	global_load_dwordx4 v[176:179], v[114:115], off nt
	global_load_dwordx4 v[180:183], v[114:115], off offset:1024 nt
	global_load_dwordx4 v[184:187], v[114:115], off offset:2048 nt
	global_load_dwordx4 v[188:191], v[114:115], off offset:3072 nt
	s_mov_b64 s[6:7], 0x3000
	v_lshl_add_u64 v[112:113], v[84:85], 0, s[6:7]
	global_load_dwordx4 v[192:195], v[112:113], off nt
	global_load_dwordx4 v[196:199], v[112:113], off offset:1024 nt
	global_load_dwordx4 v[200:203], v[112:113], off offset:2048 nt
	global_load_dwordx4 v[204:207], v[112:113], off offset:3072 nt
	s_mov_b64 s[6:7], 0x4000
	v_lshl_add_u64 v[114:115], v[84:85], 0, s[6:7]
	global_load_dwordx4 v[208:211], v[114:115], off nt
	global_load_dwordx4 v[212:215], v[114:115], off offset:1024 nt
	global_load_dwordx4 v[216:219], v[114:115], off offset:2048 nt
	global_load_dwordx4 v[220:223], v[114:115], off offset:3072 nt
	s_mov_b64 s[6:7], 0x5000
	v_lshl_add_u64 v[112:113], v[84:85], 0, s[6:7]
	global_load_dwordx4 v[224:227], v[112:113], off nt
	global_load_dwordx4 v[228:231], v[112:113], off offset:1024 nt
	global_load_dwordx4 v[232:235], v[112:113], off offset:2048 nt
	global_load_dwordx4 v[236:239], v[112:113], off offset:3072 nt
	s_mov_b64 s[6:7], 0x6000
	v_lshl_add_u64 v[114:115], v[84:85], 0, s[6:7]
	global_load_dwordx4 v[240:243], v[114:115], off nt
	global_load_dwordx4 v[244:247], v[114:115], off offset:1024 nt
	global_load_dwordx4 v[248:251], v[114:115], off offset:2048 nt
	global_load_dwordx4 v[124:127], v[114:115], off offset:3072 nt
	s_mov_b64 s[6:7], 0x7000
	v_lshl_add_u64 v[112:113], v[84:85], 0, s[6:7]
	global_load_dwordx4 v[128:131], v[112:113], off nt
	global_load_dwordx4 v[132:135], v[112:113], off offset:1024 nt
	global_load_dwordx4 v[136:139], v[112:113], off offset:2048 nt
	global_load_dwordx4 v[140:143], v[112:113], off offset:3072 nt
	s_waitcnt vmcnt(32)
	v_pk_add_f32 v[90:91], v[90:91], 1.0 op_sel_hi:[1,0]
	v_pk_add_f32 v[112:113], v[88:89], 1.0 op_sel_hi:[1,0]
	v_pk_add_f32 v[94:95], v[94:95], 1.0 op_sel_hi:[1,0]
	v_pk_add_f32 v[114:115], v[92:93], 1.0 op_sel_hi:[1,0]
	v_pk_add_f32 v[98:99], v[98:99], 1.0 op_sel_hi:[1,0]
	v_pk_add_f32 v[116:117], v[96:97], 1.0 op_sel_hi:[1,0]
	v_pk_add_f32 v[102:103], v[102:103], 1.0 op_sel_hi:[1,0]
	v_pk_add_f32 v[118:119], v[100:101], 1.0 op_sel_hi:[1,0]
	v_pk_mul_f32 v[88:89], v[2:3], v[90:91]
	v_pk_mul_f32 v[90:91], v[0:1], v[112:113]
	v_pk_mul_f32 v[92:93], v[6:7], v[94:95]
	v_pk_mul_f32 v[94:95], v[4:5], v[114:115]
	v_pk_mul_f32 v[96:97], v[10:11], v[98:99]
	v_pk_mul_f32 v[98:99], v[8:9], v[116:117]
	v_pk_mul_f32 v[100:101], v[14:15], v[102:103]
	v_pk_mul_f32 v[102:103], v[12:13], v[118:119]
	s_waitcnt vmcnt(31)
	v_pk_mul_f32 v[116:117], v[62:63], v[62:63]
	v_pk_mul_f32 v[118:119], v[60:61], v[60:61]
	s_waitcnt vmcnt(30)
	v_pk_mul_f32 v[112:113], v[58:59], v[58:59]
	v_pk_mul_f32 v[114:115], v[56:57], v[56:57]
	v_pk_mov_b32 v[120:121], v[118:119], v[116:117] op_sel:[1,0]
	v_mov_b32_e32 v119, v117
	v_pk_add_f32 v[116:117], v[120:121], v[118:119]
	v_pk_mov_b32 v[118:119], v[114:115], v[112:113] op_sel:[1,0]
	v_mov_b32_e32 v115, v113
	v_pk_add_f32 v[112:113], v[118:119], v[114:115]
	v_pk_add_f32 v[116:117], v[116:117], v[116:117] op_sel_hi:[0,1]
	v_pk_add_f32 v[112:113], v[112:113], v[112:113] op_sel_hi:[0,1]
	s_waitcnt vmcnt(29)
	v_mul_f32_e32 v112, v44, v44
	v_pk_fma_f32 v[114:115], v[44:45], v[44:45], v[112:113] op_sel_hi:[1,1,0]
	v_mul_f32_e32 v112, v46, v46
	v_pk_fma_f32 v[118:119], v[46:47], v[46:47], v[112:113] op_sel_hi:[1,1,0]
	s_waitcnt vmcnt(28)
	v_mul_f32_e32 v114, v36, v36
	v_mul_f32_e32 v118, v37, v37
	v_mul_f32_e32 v116, v38, v38
	v_mul_f32_e32 v112, v39, v39
	v_pk_add_f32 v[114:115], v[114:115], v[118:119]
	v_pk_add_f32 v[112:113], v[116:117], v[112:113]
	v_pk_add_f32 v[112:113], v[114:115], v[112:113]
	v_add_f32_e32 v81, v112, v113
	s_nop 1
	v_add_f32_dpp v81, v81, v81 quad_perm:[1,0,3,2] row_mask:0xf bank_mask:0xf
	s_nop 1
	v_add_f32_dpp v81, v81, v81 quad_perm:[2,3,0,1] row_mask:0xf bank_mask:0xf
	s_nop 1
	v_add_f32_dpp v81, v81, v81 row_half_mirror row_mask:0xf bank_mask:0xf
	s_nop 1
	v_add_f32_dpp v81, v81, v81 row_ror:8 row_mask:0xf bank_mask:0xf
	v_mov_b32_e32 v111, v81
	s_nop 1
	v_permlane16_swap_b32_e32 v111, v81
	v_add_f32_e32 v81, v81, v111
	v_mov_b32_e32 v111, v81
	s_nop 1
	v_permlane32_swap_b32_e32 v111, v81
	v_add_f32_e32 v81, v81, v111
	v_fmamk_f32 v81, v81, 0x3a800000, v75
	v_mul_f32_e32 v111, 0x4f800000, v81
	v_cmp_gt_f32_e32 vcc, s8, v81
	s_nop 1
	v_cndmask_b32_e32 v81, v81, v111, vcc
	v_sqrt_f32_e32 v111, v81
	s_nop 0
	v_add_u32_e32 v112, -1, v111
	v_add_u32_e32 v113, 1, v111
	v_fma_f32 v114, -v112, v111, v81
	v_fma_f32 v115, -v113, v111, v81
	v_cmp_ge_f32_e64 s[0:1], 0, v114
	s_nop 1
	v_cndmask_b32_e64 v111, v111, v112, s[0:1]
	v_cmp_lt_f32_e64 s[0:1], 0, v115
	s_nop 1
	v_cndmask_b32_e64 v111, v111, v113, s[0:1]
	v_mul_f32_e32 v112, 0x37800000, v111
	v_cndmask_b32_e32 v111, v111, v112, vcc
	v_cmp_class_f32_e32 vcc, v81, v109
	s_mov_b64 s[6:7], 0x0
	v_lshl_add_u64 v[112:113], s[6:7], 1, v[86:87]
	s_nop 0
	v_cndmask_b32_e32 v81, v111, v81, vcc
	v_div_scale_f32 v111, s[0:1], v81, v81, 1.0
	v_rcp_f32_e32 v114, v111
	v_div_scale_f32 v115, vcc, 1.0, v81, 1.0
	v_fma_f32 v116, -v111, v114, 1.0
	v_fmac_f32_e32 v114, v116, v114
	v_mul_f32_e32 v116, v115, v114
	v_fma_f32 v117, -v111, v116, v115
	v_fmac_f32_e32 v116, v117, v114
	v_fma_f32 v111, -v111, v116, v115
	v_div_fmas_f32 v111, v111, v114, v116
	v_div_fixup_f32 v114, v111, v81, 1.0
	v_pk_mul_f32 v[60:61], v[60:61], v[114:115] op_sel_hi:[1,0]
	v_pk_mul_f32 v[56:57], v[56:57], v[114:115] op_sel_hi:[1,0]
	v_pk_mul_f32 v[44:45], v[44:45], v[114:115] op_sel_hi:[1,0]
	v_pk_mul_f32 v[36:37], v[36:37], v[114:115] op_sel_hi:[1,0]
	v_pk_mul_f32 v[62:63], v[62:63], v[114:115] op_sel_hi:[1,0]
	v_pk_fma_f32 v[60:61], v[90:91], v[60:61], v[16:17]
	v_pk_mul_f32 v[58:59], v[58:59], v[114:115] op_sel_hi:[1,0]
	v_pk_fma_f32 v[56:57], v[94:95], v[56:57], v[20:21]
	v_pk_mul_f32 v[46:47], v[46:47], v[114:115] op_sel_hi:[1,0]
	v_pk_fma_f32 v[44:45], v[98:99], v[44:45], v[24:25]
	v_pk_mul_f32 v[38:39], v[38:39], v[114:115] op_sel_hi:[1,0]
	v_pk_fma_f32 v[36:37], v[102:103], v[36:37], v[28:29]
	v_pk_fma_f32 v[62:63], v[88:89], v[62:63], v[18:19]
	v_cvt_pk_bf16_f32 v60, v60, v61
	v_pk_fma_f32 v[58:59], v[92:93], v[58:59], v[22:23]
	v_cvt_pk_bf16_f32 v61, v62, v63
	global_store_dwordx2 v[112:113], v[60:61], off
	v_cvt_pk_bf16_f32 v56, v56, v57
	v_cvt_pk_bf16_f32 v57, v58, v59
	global_store_dwordx2 v[112:113], v[56:57], off offset:512
	v_pk_fma_f32 v[46:47], v[96:97], v[46:47], v[26:27]
	v_cvt_pk_bf16_f32 v44, v44, v45
	v_pk_fma_f32 v[38:39], v[100:101], v[38:39], v[30:31]
	v_cvt_pk_bf16_f32 v45, v46, v47
	global_store_dwordx2 v[112:113], v[44:45], off offset:1024
	v_cvt_pk_bf16_f32 v36, v36, v37
	v_cvt_pk_bf16_f32 v37, v38, v39
	global_store_dwordx2 v[112:113], v[36:37], off offset:1536
	s_waitcnt vmcnt(31)
	v_pk_mul_f32 v[116:117], v[34:35], v[34:35]
	v_pk_mul_f32 v[118:119], v[32:33], v[32:33]
	s_waitcnt vmcnt(30)
	v_pk_mul_f32 v[112:113], v[42:43], v[42:43]
	v_pk_mul_f32 v[114:115], v[40:41], v[40:41]
	v_pk_mov_b32 v[120:121], v[118:119], v[116:117] op_sel:[1,0]
	v_mov_b32_e32 v119, v117
	v_pk_add_f32 v[116:117], v[120:121], v[118:119]
	v_pk_mov_b32 v[118:119], v[114:115], v[112:113] op_sel:[1,0]
	v_mov_b32_e32 v115, v113
	v_pk_add_f32 v[112:113], v[118:119], v[114:115]
	v_pk_add_f32 v[116:117], v[116:117], v[116:117] op_sel_hi:[0,1]
	v_pk_add_f32 v[112:113], v[112:113], v[112:113] op_sel_hi:[0,1]
	s_waitcnt vmcnt(29)
	v_mul_f32_e32 v112, v48, v48
	v_pk_fma_f32 v[114:115], v[48:49], v[48:49], v[112:113] op_sel_hi:[1,1,0]
	v_mul_f32_e32 v112, v50, v50
	v_pk_fma_f32 v[118:119], v[50:51], v[50:51], v[112:113] op_sel_hi:[1,1,0]
	s_waitcnt vmcnt(28)
	v_mul_f32_e32 v114, v52, v52
	v_mul_f32_e32 v118, v53, v53
	v_mul_f32_e32 v116, v54, v54
	v_mul_f32_e32 v112, v55, v55
	v_pk_add_f32 v[114:115], v[114:115], v[118:119]
	v_pk_add_f32 v[112:113], v[116:117], v[112:113]
	v_pk_add_f32 v[112:113], v[114:115], v[112:113]
	v_add_f32_e32 v81, v112, v113
	s_nop 1
	v_add_f32_dpp v81, v81, v81 quad_perm:[1,0,3,2] row_mask:0xf bank_mask:0xf
	s_nop 1
	v_add_f32_dpp v81, v81, v81 quad_perm:[2,3,0,1] row_mask:0xf bank_mask:0xf
	s_nop 1
	v_add_f32_dpp v81, v81, v81 row_half_mirror row_mask:0xf bank_mask:0xf
	s_nop 1
	v_add_f32_dpp v81, v81, v81 row_ror:8 row_mask:0xf bank_mask:0xf
	v_mov_b32_e32 v111, v81
	s_nop 1
	v_permlane16_swap_b32_e32 v111, v81
	v_add_f32_e32 v81, v81, v111
	v_mov_b32_e32 v111, v81
	s_nop 1
	v_permlane32_swap_b32_e32 v111, v81
	v_add_f32_e32 v81, v81, v111
	v_fmamk_f32 v81, v81, 0x3a800000, v75
	v_mul_f32_e32 v111, 0x4f800000, v81
	v_cmp_gt_f32_e32 vcc, s8, v81
	s_nop 1
	v_cndmask_b32_e32 v81, v81, v111, vcc
	v_sqrt_f32_e32 v111, v81
	s_nop 0
	v_add_u32_e32 v112, -1, v111
	v_add_u32_e32 v113, 1, v111
	v_fma_f32 v114, -v112, v111, v81
	v_fma_f32 v115, -v113, v111, v81
	v_cmp_ge_f32_e64 s[0:1], 0, v114
	s_nop 1
	v_cndmask_b32_e64 v111, v111, v112, s[0:1]
	v_cmp_lt_f32_e64 s[0:1], 0, v115
	s_nop 1
	v_cndmask_b32_e64 v111, v111, v113, s[0:1]
	v_mul_f32_e32 v112, 0x37800000, v111
	v_cndmask_b32_e32 v111, v111, v112, vcc
	v_cmp_class_f32_e32 vcc, v81, v109
	s_mov_b64 s[6:7], 0x400
	v_lshl_add_u64 v[112:113], s[6:7], 1, v[86:87]
	s_nop 0
	v_cndmask_b32_e32 v81, v111, v81, vcc
	v_div_scale_f32 v111, s[0:1], v81, v81, 1.0
	v_rcp_f32_e32 v114, v111
	v_div_scale_f32 v115, vcc, 1.0, v81, 1.0
	v_fma_f32 v116, -v111, v114, 1.0
	v_fmac_f32_e32 v114, v116, v114
	v_mul_f32_e32 v116, v115, v114
	v_fma_f32 v117, -v111, v116, v115
	v_fmac_f32_e32 v116, v117, v114
	v_fma_f32 v111, -v111, v116, v115
	v_div_fmas_f32 v111, v111, v114, v116
	v_div_fixup_f32 v114, v111, v81, 1.0
	v_pk_mul_f32 v[32:33], v[32:33], v[114:115] op_sel_hi:[1,0]
	v_pk_mul_f32 v[40:41], v[40:41], v[114:115] op_sel_hi:[1,0]
	v_pk_mul_f32 v[48:49], v[48:49], v[114:115] op_sel_hi:[1,0]
	v_pk_mul_f32 v[52:53], v[52:53], v[114:115] op_sel_hi:[1,0]
	v_pk_mul_f32 v[34:35], v[34:35], v[114:115] op_sel_hi:[1,0]
	v_pk_fma_f32 v[32:33], v[90:91], v[32:33], v[16:17]
	v_pk_mul_f32 v[42:43], v[42:43], v[114:115] op_sel_hi:[1,0]
	v_pk_fma_f32 v[40:41], v[94:95], v[40:41], v[20:21]
	v_pk_mul_f32 v[50:51], v[50:51], v[114:115] op_sel_hi:[1,0]
	v_pk_fma_f32 v[48:49], v[98:99], v[48:49], v[24:25]
	v_pk_mul_f32 v[54:55], v[54:55], v[114:115] op_sel_hi:[1,0]
	v_pk_fma_f32 v[52:53], v[102:103], v[52:53], v[28:29]
	v_pk_fma_f32 v[34:35], v[88:89], v[34:35], v[18:19]
	v_cvt_pk_bf16_f32 v32, v32, v33
	v_pk_fma_f32 v[42:43], v[92:93], v[42:43], v[22:23]
	v_cvt_pk_bf16_f32 v33, v34, v35
	global_store_dwordx2 v[112:113], v[32:33], off
	v_cvt_pk_bf16_f32 v40, v40, v41
	v_cvt_pk_bf16_f32 v41, v42, v43
	global_store_dwordx2 v[112:113], v[40:41], off offset:512
	v_pk_fma_f32 v[50:51], v[96:97], v[50:51], v[26:27]
	v_cvt_pk_bf16_f32 v48, v48, v49
	v_pk_fma_f32 v[54:55], v[100:101], v[54:55], v[30:31]
	v_cvt_pk_bf16_f32 v49, v50, v51
	global_store_dwordx2 v[112:113], v[48:49], off offset:1024
	v_cvt_pk_bf16_f32 v52, v52, v53
	v_cvt_pk_bf16_f32 v53, v54, v55
	global_store_dwordx2 v[112:113], v[52:53], off offset:1536
	s_waitcnt vmcnt(31)
	v_pk_mul_f32 v[116:117], v[178:179], v[178:179]
	v_pk_mul_f32 v[118:119], v[176:177], v[176:177]
	s_waitcnt vmcnt(30)
	v_pk_mul_f32 v[112:113], v[182:183], v[182:183]
	v_pk_mul_f32 v[114:115], v[180:181], v[180:181]
	v_pk_mov_b32 v[120:121], v[118:119], v[116:117] op_sel:[1,0]
	v_mov_b32_e32 v119, v117
	v_pk_add_f32 v[116:117], v[120:121], v[118:119]
	v_pk_mov_b32 v[118:119], v[114:115], v[112:113] op_sel:[1,0]
	v_mov_b32_e32 v115, v113
	v_pk_add_f32 v[112:113], v[118:119], v[114:115]
	v_pk_add_f32 v[116:117], v[116:117], v[116:117] op_sel_hi:[0,1]
	v_pk_add_f32 v[112:113], v[112:113], v[112:113] op_sel_hi:[0,1]
	s_waitcnt vmcnt(29)
	v_mul_f32_e32 v112, v184, v184
	v_pk_fma_f32 v[114:115], v[184:185], v[184:185], v[112:113] op_sel_hi:[1,1,0]
	v_mul_f32_e32 v112, v186, v186
	v_pk_fma_f32 v[118:119], v[186:187], v[186:187], v[112:113] op_sel_hi:[1,1,0]
	s_waitcnt vmcnt(28)
	v_mul_f32_e32 v114, v188, v188
	v_mul_f32_e32 v118, v189, v189
	v_mul_f32_e32 v116, v190, v190
	v_mul_f32_e32 v112, v191, v191
	v_pk_add_f32 v[114:115], v[114:115], v[118:119]
	v_pk_add_f32 v[112:113], v[116:117], v[112:113]
	v_pk_add_f32 v[112:113], v[114:115], v[112:113]
	v_add_f32_e32 v81, v112, v113
	s_nop 1
	v_add_f32_dpp v81, v81, v81 quad_perm:[1,0,3,2] row_mask:0xf bank_mask:0xf
	s_nop 1
	v_add_f32_dpp v81, v81, v81 quad_perm:[2,3,0,1] row_mask:0xf bank_mask:0xf
	s_nop 1
	v_add_f32_dpp v81, v81, v81 row_half_mirror row_mask:0xf bank_mask:0xf
	s_nop 1
	v_add_f32_dpp v81, v81, v81 row_ror:8 row_mask:0xf bank_mask:0xf
	v_mov_b32_e32 v111, v81
	s_nop 1
	v_permlane16_swap_b32_e32 v111, v81
	v_add_f32_e32 v81, v81, v111
	v_mov_b32_e32 v111, v81
	s_nop 1
	v_permlane32_swap_b32_e32 v111, v81
	v_add_f32_e32 v81, v81, v111
	v_fmamk_f32 v81, v81, 0x3a800000, v75
	v_mul_f32_e32 v111, 0x4f800000, v81
	v_cmp_gt_f32_e32 vcc, s8, v81
	s_nop 1
	v_cndmask_b32_e32 v81, v81, v111, vcc
	v_sqrt_f32_e32 v111, v81
	s_nop 0
	v_add_u32_e32 v112, -1, v111
	v_add_u32_e32 v113, 1, v111
	v_fma_f32 v114, -v112, v111, v81
	v_fma_f32 v115, -v113, v111, v81
	v_cmp_ge_f32_e64 s[0:1], 0, v114
	s_nop 1
	v_cndmask_b32_e64 v111, v111, v112, s[0:1]
	v_cmp_lt_f32_e64 s[0:1], 0, v115
	s_nop 1
	v_cndmask_b32_e64 v111, v111, v113, s[0:1]
	v_mul_f32_e32 v112, 0x37800000, v111
	v_cndmask_b32_e32 v111, v111, v112, vcc
	v_cmp_class_f32_e32 vcc, v81, v109
	s_mov_b64 s[6:7], 0x800
	v_lshl_add_u64 v[112:113], s[6:7], 1, v[86:87]
	s_nop 0
	v_cndmask_b32_e32 v81, v111, v81, vcc
	v_div_scale_f32 v111, s[0:1], v81, v81, 1.0
	v_rcp_f32_e32 v114, v111
	v_div_scale_f32 v115, vcc, 1.0, v81, 1.0
	v_fma_f32 v116, -v111, v114, 1.0
	v_fmac_f32_e32 v114, v116, v114
	v_mul_f32_e32 v116, v115, v114
	v_fma_f32 v117, -v111, v116, v115
	v_fmac_f32_e32 v116, v117, v114
	v_fma_f32 v111, -v111, v116, v115
	v_div_fmas_f32 v111, v111, v114, v116
	v_div_fixup_f32 v114, v111, v81, 1.0
	v_pk_mul_f32 v[176:177], v[176:177], v[114:115] op_sel_hi:[1,0]
	v_pk_mul_f32 v[180:181], v[180:181], v[114:115] op_sel_hi:[1,0]
	v_pk_mul_f32 v[184:185], v[184:185], v[114:115] op_sel_hi:[1,0]
	v_pk_mul_f32 v[188:189], v[188:189], v[114:115] op_sel_hi:[1,0]
	v_pk_mul_f32 v[178:179], v[178:179], v[114:115] op_sel_hi:[1,0]
	v_pk_fma_f32 v[176:177], v[90:91], v[176:177], v[16:17]
	v_pk_mul_f32 v[182:183], v[182:183], v[114:115] op_sel_hi:[1,0]
	v_pk_fma_f32 v[180:181], v[94:95], v[180:181], v[20:21]
	v_pk_mul_f32 v[186:187], v[186:187], v[114:115] op_sel_hi:[1,0]
	v_pk_fma_f32 v[184:185], v[98:99], v[184:185], v[24:25]
	v_pk_mul_f32 v[190:191], v[190:191], v[114:115] op_sel_hi:[1,0]
	v_pk_fma_f32 v[188:189], v[102:103], v[188:189], v[28:29]
	v_pk_fma_f32 v[178:179], v[88:89], v[178:179], v[18:19]
	v_cvt_pk_bf16_f32 v176, v176, v177
	v_pk_fma_f32 v[182:183], v[92:93], v[182:183], v[22:23]
	v_cvt_pk_bf16_f32 v177, v178, v179
	global_store_dwordx2 v[112:113], v[176:177], off
	v_cvt_pk_bf16_f32 v180, v180, v181
	v_cvt_pk_bf16_f32 v181, v182, v183
	global_store_dwordx2 v[112:113], v[180:181], off offset:512
	v_pk_fma_f32 v[186:187], v[96:97], v[186:187], v[26:27]
	v_cvt_pk_bf16_f32 v184, v184, v185
	v_pk_fma_f32 v[190:191], v[100:101], v[190:191], v[30:31]
	v_cvt_pk_bf16_f32 v185, v186, v187
	global_store_dwordx2 v[112:113], v[184:185], off offset:1024
	v_cvt_pk_bf16_f32 v188, v188, v189
	v_cvt_pk_bf16_f32 v189, v190, v191
	global_store_dwordx2 v[112:113], v[188:189], off offset:1536
	s_waitcnt vmcnt(31)
	v_pk_mul_f32 v[116:117], v[194:195], v[194:195]
	v_pk_mul_f32 v[118:119], v[192:193], v[192:193]
	s_waitcnt vmcnt(30)
	v_pk_mul_f32 v[112:113], v[198:199], v[198:199]
	v_pk_mul_f32 v[114:115], v[196:197], v[196:197]
	v_pk_mov_b32 v[120:121], v[118:119], v[116:117] op_sel:[1,0]
	v_mov_b32_e32 v119, v117
	v_pk_add_f32 v[116:117], v[120:121], v[118:119]
	v_pk_mov_b32 v[118:119], v[114:115], v[112:113] op_sel:[1,0]
	v_mov_b32_e32 v115, v113
	v_pk_add_f32 v[112:113], v[118:119], v[114:115]
	v_pk_add_f32 v[116:117], v[116:117], v[116:117] op_sel_hi:[0,1]
	v_pk_add_f32 v[112:113], v[112:113], v[112:113] op_sel_hi:[0,1]
	s_waitcnt vmcnt(29)
	v_mul_f32_e32 v112, v200, v200
	v_pk_fma_f32 v[114:115], v[200:201], v[200:201], v[112:113] op_sel_hi:[1,1,0]
	v_mul_f32_e32 v112, v202, v202
	v_pk_fma_f32 v[118:119], v[202:203], v[202:203], v[112:113] op_sel_hi:[1,1,0]
	s_waitcnt vmcnt(28)
	v_mul_f32_e32 v114, v204, v204
	v_mul_f32_e32 v118, v205, v205
	v_mul_f32_e32 v116, v206, v206
	v_mul_f32_e32 v112, v207, v207
	v_pk_add_f32 v[114:115], v[114:115], v[118:119]
	v_pk_add_f32 v[112:113], v[116:117], v[112:113]
	v_pk_add_f32 v[112:113], v[114:115], v[112:113]
	v_add_f32_e32 v81, v112, v113
	s_nop 1
	v_add_f32_dpp v81, v81, v81 quad_perm:[1,0,3,2] row_mask:0xf bank_mask:0xf
	s_nop 1
	v_add_f32_dpp v81, v81, v81 quad_perm:[2,3,0,1] row_mask:0xf bank_mask:0xf
	s_nop 1
	v_add_f32_dpp v81, v81, v81 row_half_mirror row_mask:0xf bank_mask:0xf
	s_nop 1
	v_add_f32_dpp v81, v81, v81 row_ror:8 row_mask:0xf bank_mask:0xf
	v_mov_b32_e32 v111, v81
	s_nop 1
	v_permlane16_swap_b32_e32 v111, v81
	v_add_f32_e32 v81, v81, v111
	v_mov_b32_e32 v111, v81
	s_nop 1
	v_permlane32_swap_b32_e32 v111, v81
	v_add_f32_e32 v81, v81, v111
	v_fmamk_f32 v81, v81, 0x3a800000, v75
	v_mul_f32_e32 v111, 0x4f800000, v81
	v_cmp_gt_f32_e32 vcc, s8, v81
	s_nop 1
	v_cndmask_b32_e32 v81, v81, v111, vcc
	v_sqrt_f32_e32 v111, v81
	s_nop 0
	v_add_u32_e32 v112, -1, v111
	v_add_u32_e32 v113, 1, v111
	v_fma_f32 v114, -v112, v111, v81
	v_fma_f32 v115, -v113, v111, v81
	v_cmp_ge_f32_e64 s[0:1], 0, v114
	s_nop 1
	v_cndmask_b32_e64 v111, v111, v112, s[0:1]
	v_cmp_lt_f32_e64 s[0:1], 0, v115
	s_nop 1
	v_cndmask_b32_e64 v111, v111, v113, s[0:1]
	v_mul_f32_e32 v112, 0x37800000, v111
	v_cndmask_b32_e32 v111, v111, v112, vcc
	v_cmp_class_f32_e32 vcc, v81, v109
	s_mov_b64 s[6:7], 0xc00
	v_lshl_add_u64 v[112:113], s[6:7], 1, v[86:87]
	s_nop 0
	v_cndmask_b32_e32 v81, v111, v81, vcc
	v_div_scale_f32 v111, s[0:1], v81, v81, 1.0
	v_rcp_f32_e32 v114, v111
	v_div_scale_f32 v115, vcc, 1.0, v81, 1.0
	v_fma_f32 v116, -v111, v114, 1.0
	v_fmac_f32_e32 v114, v116, v114
	v_mul_f32_e32 v116, v115, v114
	v_fma_f32 v117, -v111, v116, v115
	v_fmac_f32_e32 v116, v117, v114
	v_fma_f32 v111, -v111, v116, v115
	v_div_fmas_f32 v111, v111, v114, v116
	v_div_fixup_f32 v114, v111, v81, 1.0
	v_pk_mul_f32 v[192:193], v[192:193], v[114:115] op_sel_hi:[1,0]
	v_pk_mul_f32 v[196:197], v[196:197], v[114:115] op_sel_hi:[1,0]
	v_pk_mul_f32 v[200:201], v[200:201], v[114:115] op_sel_hi:[1,0]
	v_pk_mul_f32 v[204:205], v[204:205], v[114:115] op_sel_hi:[1,0]
	v_pk_mul_f32 v[194:195], v[194:195], v[114:115] op_sel_hi:[1,0]
	v_pk_fma_f32 v[192:193], v[90:91], v[192:193], v[16:17]
	v_pk_mul_f32 v[198:199], v[198:199], v[114:115] op_sel_hi:[1,0]
	v_pk_fma_f32 v[196:197], v[94:95], v[196:197], v[20:21]
	v_pk_mul_f32 v[202:203], v[202:203], v[114:115] op_sel_hi:[1,0]
	v_pk_fma_f32 v[200:201], v[98:99], v[200:201], v[24:25]
	v_pk_mul_f32 v[206:207], v[206:207], v[114:115] op_sel_hi:[1,0]
	v_pk_fma_f32 v[204:205], v[102:103], v[204:205], v[28:29]
	v_pk_fma_f32 v[194:195], v[88:89], v[194:195], v[18:19]
	v_cvt_pk_bf16_f32 v192, v192, v193
	v_pk_fma_f32 v[198:199], v[92:93], v[198:199], v[22:23]
	v_cvt_pk_bf16_f32 v193, v194, v195
	global_store_dwordx2 v[112:113], v[192:193], off
	v_cvt_pk_bf16_f32 v196, v196, v197
	v_cvt_pk_bf16_f32 v197, v198, v199
	global_store_dwordx2 v[112:113], v[196:197], off offset:512
	v_pk_fma_f32 v[202:203], v[96:97], v[202:203], v[26:27]
	v_cvt_pk_bf16_f32 v200, v200, v201
	v_pk_fma_f32 v[206:207], v[100:101], v[206:207], v[30:31]
	v_cvt_pk_bf16_f32 v201, v202, v203
	global_store_dwordx2 v[112:113], v[200:201], off offset:1024
	v_cvt_pk_bf16_f32 v204, v204, v205
	v_cvt_pk_bf16_f32 v205, v206, v207
	global_store_dwordx2 v[112:113], v[204:205], off offset:1536
	s_waitcnt vmcnt(31)
	v_pk_mul_f32 v[116:117], v[210:211], v[210:211]
	v_pk_mul_f32 v[118:119], v[208:209], v[208:209]
	s_waitcnt vmcnt(30)
	v_pk_mul_f32 v[112:113], v[214:215], v[214:215]
	v_pk_mul_f32 v[114:115], v[212:213], v[212:213]
	v_pk_mov_b32 v[120:121], v[118:119], v[116:117] op_sel:[1,0]
	v_mov_b32_e32 v119, v117
	v_pk_add_f32 v[116:117], v[120:121], v[118:119]
	v_pk_mov_b32 v[118:119], v[114:115], v[112:113] op_sel:[1,0]
	v_mov_b32_e32 v115, v113
	v_pk_add_f32 v[112:113], v[118:119], v[114:115]
	v_pk_add_f32 v[116:117], v[116:117], v[116:117] op_sel_hi:[0,1]
	v_pk_add_f32 v[112:113], v[112:113], v[112:113] op_sel_hi:[0,1]
	s_waitcnt vmcnt(29)
	v_mul_f32_e32 v112, v216, v216
	v_pk_fma_f32 v[114:115], v[216:217], v[216:217], v[112:113] op_sel_hi:[1,1,0]
	v_mul_f32_e32 v112, v218, v218
	v_pk_fma_f32 v[118:119], v[218:219], v[218:219], v[112:113] op_sel_hi:[1,1,0]
	s_waitcnt vmcnt(28)
	v_mul_f32_e32 v114, v220, v220
	v_mul_f32_e32 v118, v221, v221
	v_mul_f32_e32 v116, v222, v222
	v_mul_f32_e32 v112, v223, v223
	v_pk_add_f32 v[114:115], v[114:115], v[118:119]
	v_pk_add_f32 v[112:113], v[116:117], v[112:113]
	v_pk_add_f32 v[112:113], v[114:115], v[112:113]
	v_add_f32_e32 v81, v112, v113
	s_nop 1
	v_add_f32_dpp v81, v81, v81 quad_perm:[1,0,3,2] row_mask:0xf bank_mask:0xf
	s_nop 1
	v_add_f32_dpp v81, v81, v81 quad_perm:[2,3,0,1] row_mask:0xf bank_mask:0xf
	s_nop 1
	v_add_f32_dpp v81, v81, v81 row_half_mirror row_mask:0xf bank_mask:0xf
	s_nop 1
	v_add_f32_dpp v81, v81, v81 row_ror:8 row_mask:0xf bank_mask:0xf
	v_mov_b32_e32 v111, v81
	s_nop 1
	v_permlane16_swap_b32_e32 v111, v81
	v_add_f32_e32 v81, v81, v111
	v_mov_b32_e32 v111, v81
	s_nop 1
	v_permlane32_swap_b32_e32 v111, v81
	v_add_f32_e32 v81, v81, v111
	v_fmamk_f32 v81, v81, 0x3a800000, v75
	v_mul_f32_e32 v111, 0x4f800000, v81
	v_cmp_gt_f32_e32 vcc, s8, v81
	s_nop 1
	v_cndmask_b32_e32 v81, v81, v111, vcc
	v_sqrt_f32_e32 v111, v81
	s_nop 0
	v_add_u32_e32 v112, -1, v111
	v_add_u32_e32 v113, 1, v111
	v_fma_f32 v114, -v112, v111, v81
	v_fma_f32 v115, -v113, v111, v81
	v_cmp_ge_f32_e64 s[0:1], 0, v114
	s_nop 1
	v_cndmask_b32_e64 v111, v111, v112, s[0:1]
	v_cmp_lt_f32_e64 s[0:1], 0, v115
	s_nop 1
	v_cndmask_b32_e64 v111, v111, v113, s[0:1]
	v_mul_f32_e32 v112, 0x37800000, v111
	v_cndmask_b32_e32 v111, v111, v112, vcc
	v_cmp_class_f32_e32 vcc, v81, v109
	s_mov_b64 s[6:7], 0x1000
	v_lshl_add_u64 v[112:113], s[6:7], 1, v[86:87]
	s_nop 0
	v_cndmask_b32_e32 v81, v111, v81, vcc
	v_div_scale_f32 v111, s[0:1], v81, v81, 1.0
	v_rcp_f32_e32 v114, v111
	v_div_scale_f32 v115, vcc, 1.0, v81, 1.0
	v_fma_f32 v116, -v111, v114, 1.0
	v_fmac_f32_e32 v114, v116, v114
	v_mul_f32_e32 v116, v115, v114
	v_fma_f32 v117, -v111, v116, v115
	v_fmac_f32_e32 v116, v117, v114
	v_fma_f32 v111, -v111, v116, v115
	v_div_fmas_f32 v111, v111, v114, v116
	v_div_fixup_f32 v114, v111, v81, 1.0
	v_pk_mul_f32 v[208:209], v[208:209], v[114:115] op_sel_hi:[1,0]
	v_pk_mul_f32 v[212:213], v[212:213], v[114:115] op_sel_hi:[1,0]
	v_pk_mul_f32 v[216:217], v[216:217], v[114:115] op_sel_hi:[1,0]
	v_pk_mul_f32 v[220:221], v[220:221], v[114:115] op_sel_hi:[1,0]
	v_pk_mul_f32 v[210:211], v[210:211], v[114:115] op_sel_hi:[1,0]
	v_pk_fma_f32 v[208:209], v[90:91], v[208:209], v[16:17]
	v_pk_mul_f32 v[214:215], v[214:215], v[114:115] op_sel_hi:[1,0]
	v_pk_fma_f32 v[212:213], v[94:95], v[212:213], v[20:21]
	v_pk_mul_f32 v[218:219], v[218:219], v[114:115] op_sel_hi:[1,0]
	v_pk_fma_f32 v[216:217], v[98:99], v[216:217], v[24:25]
	v_pk_mul_f32 v[222:223], v[222:223], v[114:115] op_sel_hi:[1,0]
	v_pk_fma_f32 v[220:221], v[102:103], v[220:221], v[28:29]
	v_pk_fma_f32 v[210:211], v[88:89], v[210:211], v[18:19]
	v_cvt_pk_bf16_f32 v208, v208, v209
	v_pk_fma_f32 v[214:215], v[92:93], v[214:215], v[22:23]
	v_cvt_pk_bf16_f32 v209, v210, v211
	global_store_dwordx2 v[112:113], v[208:209], off
	v_cvt_pk_bf16_f32 v212, v212, v213
	v_cvt_pk_bf16_f32 v213, v214, v215
	global_store_dwordx2 v[112:113], v[212:213], off offset:512
	v_pk_fma_f32 v[218:219], v[96:97], v[218:219], v[26:27]
	v_cvt_pk_bf16_f32 v216, v216, v217
	v_pk_fma_f32 v[222:223], v[100:101], v[222:223], v[30:31]
	v_cvt_pk_bf16_f32 v217, v218, v219
	global_store_dwordx2 v[112:113], v[216:217], off offset:1024
	v_cvt_pk_bf16_f32 v220, v220, v221
	v_cvt_pk_bf16_f32 v221, v222, v223
	global_store_dwordx2 v[112:113], v[220:221], off offset:1536
	s_waitcnt vmcnt(31)
	v_pk_mul_f32 v[116:117], v[226:227], v[226:227]
	v_pk_mul_f32 v[118:119], v[224:225], v[224:225]
	s_waitcnt vmcnt(30)
	v_pk_mul_f32 v[112:113], v[230:231], v[230:231]
	v_pk_mul_f32 v[114:115], v[228:229], v[228:229]
	v_pk_mov_b32 v[120:121], v[118:119], v[116:117] op_sel:[1,0]
	v_mov_b32_e32 v119, v117
	v_pk_add_f32 v[116:117], v[120:121], v[118:119]
	v_pk_mov_b32 v[118:119], v[114:115], v[112:113] op_sel:[1,0]
	v_mov_b32_e32 v115, v113
	v_pk_add_f32 v[112:113], v[118:119], v[114:115]
	v_pk_add_f32 v[116:117], v[116:117], v[116:117] op_sel_hi:[0,1]
	v_pk_add_f32 v[112:113], v[112:113], v[112:113] op_sel_hi:[0,1]
	s_waitcnt vmcnt(29)
	v_mul_f32_e32 v112, v232, v232
	v_pk_fma_f32 v[114:115], v[232:233], v[232:233], v[112:113] op_sel_hi:[1,1,0]
	v_mul_f32_e32 v112, v234, v234
	v_pk_fma_f32 v[118:119], v[234:235], v[234:235], v[112:113] op_sel_hi:[1,1,0]
	s_waitcnt vmcnt(28)
	v_mul_f32_e32 v114, v236, v236
	v_mul_f32_e32 v118, v237, v237
	v_mul_f32_e32 v116, v238, v238
	v_mul_f32_e32 v112, v239, v239
	v_pk_add_f32 v[114:115], v[114:115], v[118:119]
	v_pk_add_f32 v[112:113], v[116:117], v[112:113]
	v_pk_add_f32 v[112:113], v[114:115], v[112:113]
	v_add_f32_e32 v81, v112, v113
	s_nop 1
	v_add_f32_dpp v81, v81, v81 quad_perm:[1,0,3,2] row_mask:0xf bank_mask:0xf
	s_nop 1
	v_add_f32_dpp v81, v81, v81 quad_perm:[2,3,0,1] row_mask:0xf bank_mask:0xf
	s_nop 1
	v_add_f32_dpp v81, v81, v81 row_half_mirror row_mask:0xf bank_mask:0xf
	s_nop 1
	v_add_f32_dpp v81, v81, v81 row_ror:8 row_mask:0xf bank_mask:0xf
	v_mov_b32_e32 v111, v81
	s_nop 1
	v_permlane16_swap_b32_e32 v111, v81
	v_add_f32_e32 v81, v81, v111
	v_mov_b32_e32 v111, v81
	s_nop 1
	v_permlane32_swap_b32_e32 v111, v81
	v_add_f32_e32 v81, v81, v111
	v_fmamk_f32 v81, v81, 0x3a800000, v75
	v_mul_f32_e32 v111, 0x4f800000, v81
	v_cmp_gt_f32_e32 vcc, s8, v81
	s_nop 1
	v_cndmask_b32_e32 v81, v81, v111, vcc
	v_sqrt_f32_e32 v111, v81
	s_nop 0
	v_add_u32_e32 v112, -1, v111
	v_add_u32_e32 v113, 1, v111
	v_fma_f32 v114, -v112, v111, v81
	v_fma_f32 v115, -v113, v111, v81
	v_cmp_ge_f32_e64 s[0:1], 0, v114
	s_nop 1
	v_cndmask_b32_e64 v111, v111, v112, s[0:1]
	v_cmp_lt_f32_e64 s[0:1], 0, v115
	s_nop 1
	v_cndmask_b32_e64 v111, v111, v113, s[0:1]
	v_mul_f32_e32 v112, 0x37800000, v111
	v_cndmask_b32_e32 v111, v111, v112, vcc
	v_cmp_class_f32_e32 vcc, v81, v109
	s_mov_b64 s[6:7], 0x1400
	v_lshl_add_u64 v[112:113], s[6:7], 1, v[86:87]
	s_nop 0
	v_cndmask_b32_e32 v81, v111, v81, vcc
	v_div_scale_f32 v111, s[0:1], v81, v81, 1.0
	v_rcp_f32_e32 v114, v111
	v_div_scale_f32 v115, vcc, 1.0, v81, 1.0
	v_fma_f32 v116, -v111, v114, 1.0
	v_fmac_f32_e32 v114, v116, v114
	v_mul_f32_e32 v116, v115, v114
	v_fma_f32 v117, -v111, v116, v115
	v_fmac_f32_e32 v116, v117, v114
	v_fma_f32 v111, -v111, v116, v115
	v_div_fmas_f32 v111, v111, v114, v116
	v_div_fixup_f32 v114, v111, v81, 1.0
	v_pk_mul_f32 v[224:225], v[224:225], v[114:115] op_sel_hi:[1,0]
	v_pk_mul_f32 v[228:229], v[228:229], v[114:115] op_sel_hi:[1,0]
	v_pk_mul_f32 v[232:233], v[232:233], v[114:115] op_sel_hi:[1,0]
	v_pk_mul_f32 v[236:237], v[236:237], v[114:115] op_sel_hi:[1,0]
	v_pk_mul_f32 v[226:227], v[226:227], v[114:115] op_sel_hi:[1,0]
	v_pk_fma_f32 v[224:225], v[90:91], v[224:225], v[16:17]
	v_pk_mul_f32 v[230:231], v[230:231], v[114:115] op_sel_hi:[1,0]
	v_pk_fma_f32 v[228:229], v[94:95], v[228:229], v[20:21]
	v_pk_mul_f32 v[234:235], v[234:235], v[114:115] op_sel_hi:[1,0]
	v_pk_fma_f32 v[232:233], v[98:99], v[232:233], v[24:25]
	v_pk_mul_f32 v[238:239], v[238:239], v[114:115] op_sel_hi:[1,0]
	v_pk_fma_f32 v[236:237], v[102:103], v[236:237], v[28:29]
	v_pk_fma_f32 v[226:227], v[88:89], v[226:227], v[18:19]
	v_cvt_pk_bf16_f32 v224, v224, v225
	v_pk_fma_f32 v[230:231], v[92:93], v[230:231], v[22:23]
	v_cvt_pk_bf16_f32 v225, v226, v227
	global_store_dwordx2 v[112:113], v[224:225], off
	v_cvt_pk_bf16_f32 v228, v228, v229
	v_cvt_pk_bf16_f32 v229, v230, v231
	global_store_dwordx2 v[112:113], v[228:229], off offset:512
	v_pk_fma_f32 v[234:235], v[96:97], v[234:235], v[26:27]
	v_cvt_pk_bf16_f32 v232, v232, v233
	v_pk_fma_f32 v[238:239], v[100:101], v[238:239], v[30:31]
	v_cvt_pk_bf16_f32 v233, v234, v235
	global_store_dwordx2 v[112:113], v[232:233], off offset:1024
	v_cvt_pk_bf16_f32 v236, v236, v237
	v_cvt_pk_bf16_f32 v237, v238, v239
	global_store_dwordx2 v[112:113], v[236:237], off offset:1536
	s_waitcnt vmcnt(31)
	v_pk_mul_f32 v[116:117], v[242:243], v[242:243]
	v_pk_mul_f32 v[118:119], v[240:241], v[240:241]
	s_waitcnt vmcnt(30)
	v_pk_mul_f32 v[112:113], v[246:247], v[246:247]
	v_pk_mul_f32 v[114:115], v[244:245], v[244:245]
	v_pk_mov_b32 v[120:121], v[118:119], v[116:117] op_sel:[1,0]
	v_mov_b32_e32 v119, v117
	v_pk_add_f32 v[116:117], v[120:121], v[118:119]
	v_pk_mov_b32 v[118:119], v[114:115], v[112:113] op_sel:[1,0]
	v_mov_b32_e32 v115, v113
	v_pk_add_f32 v[112:113], v[118:119], v[114:115]
	v_pk_add_f32 v[116:117], v[116:117], v[116:117] op_sel_hi:[0,1]
	v_pk_add_f32 v[112:113], v[112:113], v[112:113] op_sel_hi:[0,1]
	s_waitcnt vmcnt(29)
	v_mul_f32_e32 v112, v248, v248
	v_pk_fma_f32 v[114:115], v[248:249], v[248:249], v[112:113] op_sel_hi:[1,1,0]
	v_mul_f32_e32 v112, v250, v250
	v_pk_fma_f32 v[118:119], v[250:251], v[250:251], v[112:113] op_sel_hi:[1,1,0]
	s_waitcnt vmcnt(28)
	v_mul_f32_e32 v114, v124, v124
	v_mul_f32_e32 v118, v125, v125
	v_mul_f32_e32 v116, v126, v126
	v_mul_f32_e32 v112, v127, v127
	v_pk_add_f32 v[114:115], v[114:115], v[118:119]
	v_pk_add_f32 v[112:113], v[116:117], v[112:113]
	v_pk_add_f32 v[112:113], v[114:115], v[112:113]
	v_add_f32_e32 v81, v112, v113
	s_nop 1
	v_add_f32_dpp v81, v81, v81 quad_perm:[1,0,3,2] row_mask:0xf bank_mask:0xf
	s_nop 1
	v_add_f32_dpp v81, v81, v81 quad_perm:[2,3,0,1] row_mask:0xf bank_mask:0xf
	s_nop 1
	v_add_f32_dpp v81, v81, v81 row_half_mirror row_mask:0xf bank_mask:0xf
	s_nop 1
	v_add_f32_dpp v81, v81, v81 row_ror:8 row_mask:0xf bank_mask:0xf
	v_mov_b32_e32 v111, v81
	s_nop 1
	v_permlane16_swap_b32_e32 v111, v81
	v_add_f32_e32 v81, v81, v111
	v_mov_b32_e32 v111, v81
	s_nop 1
	v_permlane32_swap_b32_e32 v111, v81
	v_add_f32_e32 v81, v81, v111
	v_fmamk_f32 v81, v81, 0x3a800000, v75
	v_mul_f32_e32 v111, 0x4f800000, v81
	v_cmp_gt_f32_e32 vcc, s8, v81
	s_nop 1
	v_cndmask_b32_e32 v81, v81, v111, vcc
	v_sqrt_f32_e32 v111, v81
	s_nop 0
	v_add_u32_e32 v112, -1, v111
	v_add_u32_e32 v113, 1, v111
	v_fma_f32 v114, -v112, v111, v81
	v_fma_f32 v115, -v113, v111, v81
	v_cmp_ge_f32_e64 s[0:1], 0, v114
	s_nop 1
	v_cndmask_b32_e64 v111, v111, v112, s[0:1]
	v_cmp_lt_f32_e64 s[0:1], 0, v115
	s_nop 1
	v_cndmask_b32_e64 v111, v111, v113, s[0:1]
	v_mul_f32_e32 v112, 0x37800000, v111
	v_cndmask_b32_e32 v111, v111, v112, vcc
	v_cmp_class_f32_e32 vcc, v81, v109
	s_mov_b64 s[6:7], 0x1800
	v_lshl_add_u64 v[112:113], s[6:7], 1, v[86:87]
	s_nop 0
	v_cndmask_b32_e32 v81, v111, v81, vcc
	v_div_scale_f32 v111, s[0:1], v81, v81, 1.0
	v_rcp_f32_e32 v114, v111
	v_div_scale_f32 v115, vcc, 1.0, v81, 1.0
	v_fma_f32 v116, -v111, v114, 1.0
	v_fmac_f32_e32 v114, v116, v114
	v_mul_f32_e32 v116, v115, v114
	v_fma_f32 v117, -v111, v116, v115
	v_fmac_f32_e32 v116, v117, v114
	v_fma_f32 v111, -v111, v116, v115
	v_div_fmas_f32 v111, v111, v114, v116
	v_div_fixup_f32 v114, v111, v81, 1.0
	v_pk_mul_f32 v[240:241], v[240:241], v[114:115] op_sel_hi:[1,0]
	v_pk_mul_f32 v[244:245], v[244:245], v[114:115] op_sel_hi:[1,0]
	v_pk_mul_f32 v[248:249], v[248:249], v[114:115] op_sel_hi:[1,0]
	v_pk_mul_f32 v[124:125], v[124:125], v[114:115] op_sel_hi:[1,0]
	v_pk_mul_f32 v[242:243], v[242:243], v[114:115] op_sel_hi:[1,0]
	v_pk_fma_f32 v[240:241], v[90:91], v[240:241], v[16:17]
	v_pk_mul_f32 v[246:247], v[246:247], v[114:115] op_sel_hi:[1,0]
	v_pk_fma_f32 v[244:245], v[94:95], v[244:245], v[20:21]
	v_pk_mul_f32 v[250:251], v[250:251], v[114:115] op_sel_hi:[1,0]
	v_pk_fma_f32 v[248:249], v[98:99], v[248:249], v[24:25]
	v_pk_mul_f32 v[126:127], v[126:127], v[114:115] op_sel_hi:[1,0]
	v_pk_fma_f32 v[124:125], v[102:103], v[124:125], v[28:29]
	v_pk_fma_f32 v[242:243], v[88:89], v[242:243], v[18:19]
	v_cvt_pk_bf16_f32 v240, v240, v241
	v_pk_fma_f32 v[246:247], v[92:93], v[246:247], v[22:23]
	v_cvt_pk_bf16_f32 v241, v242, v243
	global_store_dwordx2 v[112:113], v[240:241], off
	v_cvt_pk_bf16_f32 v244, v244, v245
	v_cvt_pk_bf16_f32 v245, v246, v247
	global_store_dwordx2 v[112:113], v[244:245], off offset:512
	v_pk_fma_f32 v[250:251], v[96:97], v[250:251], v[26:27]
	v_cvt_pk_bf16_f32 v248, v248, v249
	v_pk_fma_f32 v[126:127], v[100:101], v[126:127], v[30:31]
	v_cvt_pk_bf16_f32 v249, v250, v251
	global_store_dwordx2 v[112:113], v[248:249], off offset:1024
	v_cvt_pk_bf16_f32 v124, v124, v125
	v_cvt_pk_bf16_f32 v125, v126, v127
	global_store_dwordx2 v[112:113], v[124:125], off offset:1536
	s_waitcnt vmcnt(31)
	v_pk_mul_f32 v[116:117], v[130:131], v[130:131]
	v_pk_mul_f32 v[118:119], v[128:129], v[128:129]
	s_waitcnt vmcnt(30)
	v_pk_mul_f32 v[112:113], v[134:135], v[134:135]
	v_pk_mul_f32 v[114:115], v[132:133], v[132:133]
	v_pk_mov_b32 v[120:121], v[118:119], v[116:117] op_sel:[1,0]
	v_mov_b32_e32 v119, v117
	v_pk_add_f32 v[116:117], v[120:121], v[118:119]
	v_pk_mov_b32 v[118:119], v[114:115], v[112:113] op_sel:[1,0]
	v_mov_b32_e32 v115, v113
	v_pk_add_f32 v[112:113], v[118:119], v[114:115]
	v_pk_add_f32 v[116:117], v[116:117], v[116:117] op_sel_hi:[0,1]
	v_pk_add_f32 v[112:113], v[112:113], v[112:113] op_sel_hi:[0,1]
	s_waitcnt vmcnt(29)
	v_mul_f32_e32 v112, v136, v136
	v_pk_fma_f32 v[114:115], v[136:137], v[136:137], v[112:113] op_sel_hi:[1,1,0]
	v_mul_f32_e32 v112, v138, v138
	v_pk_fma_f32 v[118:119], v[138:139], v[138:139], v[112:113] op_sel_hi:[1,1,0]
	s_waitcnt vmcnt(28)
	v_mul_f32_e32 v114, v140, v140
	v_mul_f32_e32 v118, v141, v141
	v_mul_f32_e32 v116, v142, v142
	v_mul_f32_e32 v112, v143, v143
	v_pk_add_f32 v[114:115], v[114:115], v[118:119]
	v_pk_add_f32 v[112:113], v[116:117], v[112:113]
	v_pk_add_f32 v[112:113], v[114:115], v[112:113]
	v_add_f32_e32 v81, v112, v113
	s_nop 1
	v_add_f32_dpp v81, v81, v81 quad_perm:[1,0,3,2] row_mask:0xf bank_mask:0xf
	s_nop 1
	v_add_f32_dpp v81, v81, v81 quad_perm:[2,3,0,1] row_mask:0xf bank_mask:0xf
	s_nop 1
	v_add_f32_dpp v81, v81, v81 row_half_mirror row_mask:0xf bank_mask:0xf
	s_nop 1
	v_add_f32_dpp v81, v81, v81 row_ror:8 row_mask:0xf bank_mask:0xf
	v_mov_b32_e32 v111, v81
	s_nop 1
	v_permlane16_swap_b32_e32 v111, v81
	v_add_f32_e32 v81, v81, v111
	v_mov_b32_e32 v111, v81
	s_nop 1
	v_permlane32_swap_b32_e32 v111, v81
	v_add_f32_e32 v81, v81, v111
	v_fmamk_f32 v81, v81, 0x3a800000, v75
	v_mul_f32_e32 v111, 0x4f800000, v81
	v_cmp_gt_f32_e32 vcc, s8, v81
	s_nop 1
	v_cndmask_b32_e32 v81, v81, v111, vcc
	v_sqrt_f32_e32 v111, v81
	s_nop 0
	v_add_u32_e32 v112, -1, v111
	v_add_u32_e32 v113, 1, v111
	v_fma_f32 v114, -v112, v111, v81
	v_fma_f32 v115, -v113, v111, v81
	v_cmp_ge_f32_e64 s[0:1], 0, v114
	s_nop 1
	v_cndmask_b32_e64 v111, v111, v112, s[0:1]
	v_cmp_lt_f32_e64 s[0:1], 0, v115
	s_nop 1
	v_cndmask_b32_e64 v111, v111, v113, s[0:1]
	v_mul_f32_e32 v112, 0x37800000, v111
	v_cndmask_b32_e32 v111, v111, v112, vcc
	v_cmp_class_f32_e32 vcc, v81, v109
	s_mov_b64 s[6:7], 0x1c00
	v_lshl_add_u64 v[112:113], s[6:7], 1, v[86:87]
	s_nop 0
	v_cndmask_b32_e32 v81, v111, v81, vcc
	v_div_scale_f32 v111, s[0:1], v81, v81, 1.0
	v_rcp_f32_e32 v114, v111
	v_div_scale_f32 v115, vcc, 1.0, v81, 1.0
	v_fma_f32 v116, -v111, v114, 1.0
	v_fmac_f32_e32 v114, v116, v114
	v_mul_f32_e32 v116, v115, v114
	v_fma_f32 v117, -v111, v116, v115
	v_fmac_f32_e32 v116, v117, v114
	v_fma_f32 v111, -v111, v116, v115
	v_div_fmas_f32 v111, v111, v114, v116
	v_div_fixup_f32 v114, v111, v81, 1.0
	v_pk_mul_f32 v[128:129], v[128:129], v[114:115] op_sel_hi:[1,0]
	v_pk_mul_f32 v[132:133], v[132:133], v[114:115] op_sel_hi:[1,0]
	v_pk_mul_f32 v[136:137], v[136:137], v[114:115] op_sel_hi:[1,0]
	v_pk_mul_f32 v[140:141], v[140:141], v[114:115] op_sel_hi:[1,0]
	v_pk_mul_f32 v[130:131], v[130:131], v[114:115] op_sel_hi:[1,0]
	v_pk_fma_f32 v[128:129], v[90:91], v[128:129], v[16:17]
	v_pk_mul_f32 v[134:135], v[134:135], v[114:115] op_sel_hi:[1,0]
	v_pk_fma_f32 v[132:133], v[94:95], v[132:133], v[20:21]
	v_pk_mul_f32 v[138:139], v[138:139], v[114:115] op_sel_hi:[1,0]
	v_pk_fma_f32 v[136:137], v[98:99], v[136:137], v[24:25]
	v_pk_mul_f32 v[142:143], v[142:143], v[114:115] op_sel_hi:[1,0]
	v_pk_fma_f32 v[140:141], v[102:103], v[140:141], v[28:29]
	v_pk_fma_f32 v[130:131], v[88:89], v[130:131], v[18:19]
	v_cvt_pk_bf16_f32 v128, v128, v129
	v_pk_fma_f32 v[134:135], v[92:93], v[134:135], v[22:23]
	v_cvt_pk_bf16_f32 v129, v130, v131
	global_store_dwordx2 v[112:113], v[128:129], off
	v_cvt_pk_bf16_f32 v132, v132, v133
	v_cvt_pk_bf16_f32 v133, v134, v135
	global_store_dwordx2 v[112:113], v[132:133], off offset:512
	v_pk_fma_f32 v[138:139], v[96:97], v[138:139], v[26:27]
	v_cvt_pk_bf16_f32 v136, v136, v137
	v_pk_fma_f32 v[142:143], v[100:101], v[142:143], v[30:31]
	v_cvt_pk_bf16_f32 v137, v138, v139
	global_store_dwordx2 v[112:113], v[136:137], off offset:1024
	v_cvt_pk_bf16_f32 v140, v140, v141
	v_cvt_pk_bf16_f32 v141, v142, v143
	global_store_dwordx2 v[112:113], v[140:141], off offset:1536
	s_branch .LBB0_249
